# v28 plus: K-fragment reads software-pipelined in all four QK blocks (A and B paths)
# baseline (speedup 1.0000x reference)
.LBB0_551:
	s_add_i32 s9, s29, 0xffffff80
	s_cmp_gt_i32 s9, s59
	s_cselect_b64 s[0:1], -1, 0
	s_add_i32 s78, s29, 0xffffffbf
	s_cmp_le_i32 s78, s60
	s_cselect_b64 s[40:41], -1, 0
	s_or_b64 s[0:1], s[0:1], s[40:41]
	s_and_b64 vcc, exec, s[0:1]
	v_add_u32_e32 v197, s29, v234
	v_readfirstlane_b32 s40, v252
	s_nop 0
	s_cmpk_ge_u32 s40, 0x100
	s_cbranch_scc1 .Lst1_b
	s_cbranch_vccnz .LBB0_553
	v_add_u32_e32 v0, 0xffffff80, v197
	v_cvt_f32_i32_e32 v0, v0
	ds_read_b128 v[2:5], v235 offset:49152
	ds_read_b128 v[6:9], v235 offset:57344
	ds_read_b128 v[10:13], v236 offset:49152
	ds_read_b128 v[18:21], v236 offset:57344
	ds_read_b128 v[22:25], v237 offset:49152
	ds_read_b128 v[26:29], v237 offset:57344
	ds_read_b128 v[96:99], v238 offset:49152
	v_mov_b32_e32 v205, v204
	v_fma_f32 v117, s61, v0, s61
	v_add_f32_e32 v118, s61, v117
	v_mul_f32_e32 v116, s61, v0
	v_add_f32_e32 v119, s61, v118
	v_pk_add_f32 v[120:121], v[206:207], v[116:117]
	v_pk_add_f32 v[122:123], v[206:207], v[118:119]
	v_pk_add_f32 v[124:125], v[206:207], v[120:121]
	v_pk_add_f32 v[126:127], v[206:207], v[122:123]
	s_waitcnt vmcnt(0)
	v_pk_add_f32 v[128:129], v[206:207], v[124:125]
	v_pk_add_f32 v[130:131], v[206:207], v[126:127]
	v_pk_add_f32 v[100:101], v[14:15], v[116:117]
	v_pk_add_f32 v[104:105], v[204:205], v[120:121]
	v_pk_add_f32 v[108:109], v[204:205], v[124:125]
	v_pk_add_f32 v[102:103], v[204:205], v[118:119]
	v_pk_add_f32 v[112:113], v[204:205], v[128:129]
	v_pk_add_f32 v[106:107], v[204:205], v[122:123]
	v_pk_add_f32 v[110:111], v[204:205], v[126:127]
	v_pk_add_f32 v[114:115], v[204:205], v[130:131]
	s_waitcnt lgkmcnt(6)
	v_mfma_f32_32x32x16_bf16 v[116:131], v[2:5], v[188:191], v[116:131]
	ds_read_b128 v[2:5], v238 offset:57344
	s_waitcnt lgkmcnt(6)
	v_mfma_f32_32x32x16_bf16 v[100:115], v[6:9], v[188:191], v[100:115]
	ds_read_b128 v[6:9], v235 offset:49280
	s_waitcnt lgkmcnt(6)
	v_mfma_f32_32x32x16_bf16 v[116:131], v[10:13], v[184:187], v[116:131]
	ds_read_b128 v[10:13], v235 offset:57472
	s_waitcnt lgkmcnt(6)
	v_mfma_f32_32x32x16_bf16 v[100:115], v[18:21], v[184:187], v[100:115]
	ds_read_b128 v[18:21], v236 offset:49280
	s_waitcnt lgkmcnt(6)
	v_mfma_f32_32x32x16_bf16 v[116:131], v[22:25], v[180:183], v[116:131]
	ds_read_b128 v[22:25], v236 offset:57472
	s_waitcnt lgkmcnt(6)
	v_mfma_f32_32x32x16_bf16 v[100:115], v[26:29], v[180:183], v[100:115]
	ds_read_b128 v[26:29], v237 offset:49280
	s_waitcnt lgkmcnt(6)
	v_mfma_f32_32x32x16_bf16 v[116:131], v[96:99], v[176:179], v[116:131]
	ds_read_b128 v[96:99], v237 offset:57472
	s_waitcnt lgkmcnt(6)
	v_mfma_f32_32x32x16_bf16 v[100:115], v[2:5], v[176:179], v[100:115]
	ds_read_b128 v[2:5], v238 offset:49280
	s_waitcnt lgkmcnt(6)
	v_mfma_f32_32x32x16_bf16 v[116:131], v[6:9], v[172:175], v[116:131]
	ds_read_b128 v[6:9], v238 offset:57472
	s_waitcnt lgkmcnt(6)
	v_mfma_f32_32x32x16_bf16 v[100:115], v[10:13], v[172:175], v[100:115]
	s_waitcnt lgkmcnt(5)
	v_mfma_f32_32x32x16_bf16 v[116:131], v[18:21], v[168:171], v[116:131]
	s_waitcnt lgkmcnt(4)
	v_mfma_f32_32x32x16_bf16 v[100:115], v[22:25], v[168:171], v[100:115]
	s_waitcnt lgkmcnt(3)
	v_mfma_f32_32x32x16_bf16 v[116:131], v[26:29], v[164:167], v[116:131]
	s_waitcnt lgkmcnt(2)
	v_mfma_f32_32x32x16_bf16 v[100:115], v[96:99], v[164:167], v[100:115]
	s_waitcnt lgkmcnt(1)
	v_mfma_f32_32x32x16_bf16 v[116:131], v[2:5], v[160:163], v[116:131]
	s_waitcnt lgkmcnt(0)
	v_mfma_f32_32x32x16_bf16 v[100:115], v[6:9], v[160:163], v[100:115]
	s_branch .LBB0_554
.Lst1_b:
	v_add_f32_e32 v0, 0, v193
	v_add_f32_e32 v0, v195, v0
	v_add_f32_e32 v0, v159, v0
	v_add_f32_e32 v0, v194, v0
	v_add_f32_e32 v0, v157, v0
	v_add_f32_e32 v0, v192, v0
	v_add_f32_e32 v0, v156, v0
	v_add_f32_e32 v0, v158, v0
	v_add_f32_e32 v0, v150, v0
	v_add_f32_e32 v0, v153, v0
	v_add_f32_e32 v0, v149, v0
	v_add_f32_e32 v0, v151, v0
	v_exp_f32_e32 v2, v146
	v_add_f32_e32 v0, v148, v0
	v_exp_f32_e32 v3, v147
	v_add_f32_e32 v0, v155, v0
	v_exp_f32_e32 v4, v144
	v_add_f32_e32 v0, v152, v0
	v_exp_f32_e32 v5, v145
	v_add_f32_e32 v0, v154, v0
	v_exp_f32_e32 v6, v132
	v_add_f32_e32 v0, v2, v0
	v_exp_f32_e32 v7, v133
	v_add_f32_e32 v0, v3, v0
	v_exp_f32_e32 v8, v134
	v_add_f32_e32 v0, v4, v0
	v_exp_f32_e32 v9, v135
	v_add_f32_e32 v0, v5, v0
	v_exp_f32_e32 v10, v136
	v_add_f32_e32 v0, v6, v0
	v_exp_f32_e32 v11, v137
	v_add_f32_e32 v0, v7, v0
	v_exp_f32_e32 v12, v138
	v_add_f32_e32 v0, v8, v0
	v_exp_f32_e32 v13, v139
	v_add_f32_e32 v0, v9, v0
	v_exp_f32_e32 v17, v140
	v_add_f32_e32 v0, v10, v0
	v_exp_f32_e32 v30, v141
	v_add_f32_e32 v0, v11, v0
	v_exp_f32_e32 v31, v142
	v_add_f32_e32 v0, v12, v0
	v_exp_f32_e32 v99, v143
	v_add_f32_e32 v0, v13, v0
	v_add_f32_e32 v0, v17, v0
	v_add_f32_e32 v0, v30, v0
	v_add_f32_e32 v0, v31, v0
	v_add_f32_e32 v0, v99, v0
	v_mov_b32_e32 v239, v0
	v_cvt_pk_bf16_f32 v18, v193, v195
	v_cvt_pk_bf16_f32 v19, v159, v194
	v_cvt_pk_bf16_f32 v20, v157, v192
	v_cvt_pk_bf16_f32 v21, v156, v158
	v_cvt_pk_bf16_f32 v22, v150, v153
	v_cvt_pk_bf16_f32 v23, v149, v151
	v_cvt_pk_bf16_f32 v24, v148, v155
	v_cvt_pk_bf16_f32 v25, v152, v154
	v_cvt_pk_bf16_f32 v26, v2, v3
	v_cvt_pk_bf16_f32 v27, v4, v5
	v_cvt_pk_bf16_f32 v28, v6, v7
	v_cvt_pk_bf16_f32 v29, v8, v9
	v_cvt_pk_bf16_f32 v96, v10, v11
	v_cvt_pk_bf16_f32 v97, v12, v13
	v_cvt_pk_bf16_f32 v98, v17, v30
	v_cvt_pk_bf16_f32 v99, v31, v99
	s_nop 1
	v_permlane32_swap_b32_e32 v0, v239
	v_permlane32_swap_b32_e32 v18, v20
	v_permlane32_swap_b32_e32 v19, v21
	v_permlane32_swap_b32_e32 v22, v24
	v_permlane32_swap_b32_e32 v23, v25
	v_permlane32_swap_b32_e32 v26, v28
	v_permlane32_swap_b32_e32 v27, v29
	v_permlane32_swap_b32_e32 v96, v98
	v_permlane32_swap_b32_e32 v97, v99
	s_and_b64 vcc, exec, s[0:1]
	s_cbranch_vccnz .Lst1_b_inact
	v_add_u32_e32 v240, 0xffffff80, v197
	v_cvt_f32_i32_e32 v240, v240
	ds_read_b128 v[2:5], v235 offset:49152
	ds_read_b128 v[6:9], v235 offset:57344
	ds_read_b128 v[10:13], v236 offset:49152
	ds_read_b128 v[244:247], v236 offset:57344
	v_mov_b32_e32 v205, v204
	v_fma_f32 v117, s61, v240, s61
	v_add_f32_e32 v118, s61, v117
	v_mul_f32_e32 v116, s61, v240
	v_add_f32_e32 v119, s61, v118
	v_pk_add_f32 v[120:121], v[206:207], v[116:117]
	v_pk_add_f32 v[122:123], v[206:207], v[118:119]
	v_pk_add_f32 v[124:125], v[206:207], v[120:121]
	v_pk_add_f32 v[126:127], v[206:207], v[122:123]
	s_waitcnt vmcnt(0)
	v_pk_add_f32 v[128:129], v[206:207], v[124:125]
	v_pk_add_f32 v[130:131], v[206:207], v[126:127]
	v_pk_add_f32 v[100:101], v[14:15], v[116:117]
	v_pk_add_f32 v[104:105], v[204:205], v[120:121]
	v_pk_add_f32 v[108:109], v[204:205], v[124:125]
	v_pk_add_f32 v[102:103], v[204:205], v[118:119]
	v_pk_add_f32 v[112:113], v[204:205], v[128:129]
	v_pk_add_f32 v[106:107], v[204:205], v[122:123]
	v_pk_add_f32 v[110:111], v[204:205], v[126:127]
	v_pk_add_f32 v[114:115], v[204:205], v[130:131]
	s_waitcnt lgkmcnt(3)
	v_mfma_f32_32x32x16_bf16 v[116:131], v[2:5], v[188:191], v[116:131]
	ds_read_b128 v[2:5], v237 offset:49152
	s_waitcnt lgkmcnt(3)
	v_mfma_f32_32x32x16_bf16 v[100:115], v[6:9], v[188:191], v[100:115]
	ds_read_b128 v[6:9], v237 offset:57344
	s_waitcnt lgkmcnt(3)
	v_mfma_f32_32x32x16_bf16 v[116:131], v[10:13], v[184:187], v[116:131]
	ds_read_b128 v[10:13], v238 offset:49152
	s_waitcnt lgkmcnt(3)
	v_mfma_f32_32x32x16_bf16 v[100:115], v[244:247], v[184:187], v[100:115]
	ds_read_b128 v[244:247], v238 offset:57344
	s_waitcnt lgkmcnt(3)
	v_mfma_f32_32x32x16_bf16 v[116:131], v[2:5], v[180:183], v[116:131]
	ds_read_b128 v[2:5], v235 offset:49280
	s_waitcnt lgkmcnt(3)
	v_mfma_f32_32x32x16_bf16 v[100:115], v[6:9], v[180:183], v[100:115]
	ds_read_b128 v[6:9], v235 offset:57472
	s_waitcnt lgkmcnt(3)
	v_mfma_f32_32x32x16_bf16 v[116:131], v[10:13], v[176:179], v[116:131]
	ds_read_b128 v[10:13], v236 offset:49280
	s_waitcnt lgkmcnt(3)
	v_mfma_f32_32x32x16_bf16 v[100:115], v[244:247], v[176:179], v[100:115]
	ds_read_b128 v[244:247], v236 offset:57472
	s_waitcnt lgkmcnt(3)
	v_mfma_f32_32x32x16_bf16 v[116:131], v[2:5], v[172:175], v[116:131]
	ds_read_b128 v[2:5], v237 offset:49280
	s_waitcnt lgkmcnt(3)
	v_mfma_f32_32x32x16_bf16 v[100:115], v[6:9], v[172:175], v[100:115]
	ds_read_b128 v[6:9], v237 offset:57472
	s_waitcnt lgkmcnt(3)
	v_mfma_f32_32x32x16_bf16 v[116:131], v[10:13], v[168:171], v[116:131]
	ds_read_b128 v[10:13], v238 offset:49280
	s_waitcnt lgkmcnt(3)
	v_mfma_f32_32x32x16_bf16 v[100:115], v[244:247], v[168:171], v[100:115]
	ds_read_b128 v[244:247], v238 offset:57472
	s_waitcnt lgkmcnt(3)
	v_mfma_f32_32x32x16_bf16 v[116:131], v[2:5], v[164:167], v[116:131]
	s_waitcnt lgkmcnt(2)
	v_mfma_f32_32x32x16_bf16 v[100:115], v[6:9], v[164:167], v[100:115]
	s_waitcnt lgkmcnt(1)
	v_mfma_f32_32x32x16_bf16 v[116:131], v[10:13], v[160:163], v[116:131]
	s_waitcnt lgkmcnt(0)
	v_mfma_f32_32x32x16_bf16 v[100:115], v[244:247], v[160:163], v[100:115]
	s_branch .Lst1_join

.LBB0_563:
	v_cndmask_b32_e64 v241, v17, v196, s[0:1]
	v_mul_f32_e32 v196, 0xbe0293ee, v241
	v_fmamk_f32 v17, v116, 0x3e0293ee, v196
	v_fmamk_f32 v18, v117, 0x3e0293ee, v196
	v_fmamk_f32 v19, v118, 0x3e0293ee, v196
	v_fmamk_f32 v20, v119, 0x3e0293ee, v196
	v_fmamk_f32 v21, v120, 0x3e0293ee, v196
	v_fmamk_f32 v22, v121, 0x3e0293ee, v196
	v_fmamk_f32 v23, v122, 0x3e0293ee, v196
	v_fmamk_f32 v24, v123, 0x3e0293ee, v196
	v_fmamk_f32 v25, v124, 0x3e0293ee, v196
	v_fmamk_f32 v26, v125, 0x3e0293ee, v196
	v_fmamk_f32 v27, v126, 0x3e0293ee, v196
	v_fmamk_f32 v28, v127, 0x3e0293ee, v196
	v_fmamk_f32 v29, v128, 0x3e0293ee, v196
	v_fmamk_f32 v30, v129, 0x3e0293ee, v196
	v_fmamk_f32 v31, v130, 0x3e0293ee, v196
	v_fmamk_f32 v128, v131, 0x3e0293ee, v196
	v_fmamk_f32 v116, v100, 0x3e0293ee, v196
	v_fmamk_f32 v117, v101, 0x3e0293ee, v196
	v_fmamk_f32 v118, v102, 0x3e0293ee, v196
	v_fmamk_f32 v119, v103, 0x3e0293ee, v196
	v_fmamk_f32 v120, v104, 0x3e0293ee, v196
	v_fmamk_f32 v121, v105, 0x3e0293ee, v196
	v_fmamk_f32 v122, v106, 0x3e0293ee, v196
	v_fmamk_f32 v123, v107, 0x3e0293ee, v196
	v_fmamk_f32 v124, v108, 0x3e0293ee, v196
	v_fmamk_f32 v125, v109, 0x3e0293ee, v196
	v_fmamk_f32 v126, v110, 0x3e0293ee, v196
	v_fmamk_f32 v127, v111, 0x3e0293ee, v196
	v_exp_f32_e32 v96, v17
	v_exp_f32_e32 v97, v18
	v_exp_f32_e32 v98, v19
	v_exp_f32_e32 v99, v20
	v_exp_f32_e32 v100, v21
	v_exp_f32_e32 v101, v22
	v_exp_f32_e32 v102, v23
	v_exp_f32_e32 v103, v24
	v_exp_f32_e32 v104, v25
	v_exp_f32_e32 v105, v26
	v_exp_f32_e32 v106, v27
	v_exp_f32_e32 v107, v28
	v_exp_f32_e32 v108, v29
	v_exp_f32_e32 v109, v30
	v_exp_f32_e32 v110, v31
	v_exp_f32_e32 v111, v128
	v_fmamk_f32 v198, v112, 0x3e0293ee, v196
	v_fmamk_f32 v199, v113, 0x3e0293ee, v196
	v_fmamk_f32 v242, v114, 0x3e0293ee, v196
	v_fmac_f32_e32 v196, 0x3e0293ee, v115
	s_waitcnt lgkmcnt(0)
	s_barrier
	s_cmp_gt_i32 s8, s59
	s_cselect_b64 s[0:1], -1, 0
	s_add_i32 s9, s29, -1
	s_cmp_le_i32 s9, s60
	s_cselect_b64 s[78:79], -1, 0
	s_or_b64 s[0:1], s[0:1], s[78:79]
	s_and_b64 vcc, exec, s[0:1]
	v_readfirstlane_b32 s78, v252
	s_nop 0
	s_cmpk_ge_u32 s78, 0x100
	s_cbranch_scc1 .Lst2_b
	s_cbranch_vccnz .LBB0_565
	v_subrev_u32_e32 v17, 64, v197
	v_cvt_f32_i32_e32 v17, v17
	ds_read_b128 v[18:21], v235 offset:32768
	ds_read_b128 v[22:25], v235 offset:40960
	ds_read_b128 v[26:29], v236 offset:32768
	ds_read_b128 v[112:115], v236 offset:40960
	ds_read_b128 v[244:247], v237 offset:32768
	v_mov_b32_e32 v205, v204
	v_fma_f32 v145, s61, v17, s61
	v_add_f32_e32 v146, s61, v145
	v_mul_f32_e32 v144, s61, v17
	v_add_f32_e32 v147, s61, v146
	v_pk_add_f32 v[148:149], v[206:207], v[144:145]
	v_pk_add_f32 v[150:151], v[206:207], v[146:147]
	v_pk_add_f32 v[152:153], v[206:207], v[148:149]
	v_pk_add_f32 v[154:155], v[206:207], v[150:151]
	v_pk_add_f32 v[156:157], v[206:207], v[152:153]
	v_pk_add_f32 v[158:159], v[206:207], v[154:155]
	v_pk_add_f32 v[128:129], v[14:15], v[144:145]
	v_pk_add_f32 v[132:133], v[204:205], v[148:149]
	v_pk_add_f32 v[136:137], v[204:205], v[152:153]
	v_pk_add_f32 v[130:131], v[204:205], v[146:147]
	v_pk_add_f32 v[140:141], v[204:205], v[156:157]
	v_pk_add_f32 v[134:135], v[204:205], v[150:151]
	v_pk_add_f32 v[138:139], v[204:205], v[154:155]
	v_pk_add_f32 v[142:143], v[204:205], v[158:159]
	s_waitcnt lgkmcnt(4)
	v_mfma_f32_32x32x16_bf16 v[144:159], v[18:21], v[188:191], v[144:159]
	ds_read_b128 v[18:21], v237 offset:40960
	s_waitcnt lgkmcnt(4)
	v_mfma_f32_32x32x16_bf16 v[128:143], v[22:25], v[188:191], v[128:143]
	ds_read_b128 v[22:25], v238 offset:32768
	s_waitcnt lgkmcnt(4)
	v_mfma_f32_32x32x16_bf16 v[144:159], v[26:29], v[184:187], v[144:159]
	ds_read_b128 v[26:29], v238 offset:40960
	s_waitcnt lgkmcnt(4)
	v_mfma_f32_32x32x16_bf16 v[128:143], v[112:115], v[184:187], v[128:143]
	ds_read_b128 v[112:115], v235 offset:32896
	s_waitcnt lgkmcnt(4)
	v_mfma_f32_32x32x16_bf16 v[144:159], v[244:247], v[180:183], v[144:159]
	ds_read_b128 v[244:247], v235 offset:41088
	s_waitcnt lgkmcnt(4)
	v_mfma_f32_32x32x16_bf16 v[128:143], v[18:21], v[180:183], v[128:143]
	ds_read_b128 v[18:21], v236 offset:32896
	s_waitcnt lgkmcnt(4)
	v_mfma_f32_32x32x16_bf16 v[144:159], v[22:25], v[176:179], v[144:159]
	ds_read_b128 v[22:25], v236 offset:41088
	s_waitcnt lgkmcnt(4)
	v_mfma_f32_32x32x16_bf16 v[128:143], v[26:29], v[176:179], v[128:143]
	ds_read_b128 v[26:29], v237 offset:32896
	s_waitcnt lgkmcnt(4)
	v_mfma_f32_32x32x16_bf16 v[144:159], v[112:115], v[172:175], v[144:159]
	ds_read_b128 v[112:115], v237 offset:41088
	s_waitcnt lgkmcnt(4)
	v_mfma_f32_32x32x16_bf16 v[128:143], v[244:247], v[172:175], v[128:143]
	ds_read_b128 v[244:247], v238 offset:32896
	s_waitcnt lgkmcnt(4)
	v_mfma_f32_32x32x16_bf16 v[144:159], v[18:21], v[168:171], v[144:159]
	ds_read_b128 v[18:21], v238 offset:41088
	s_waitcnt lgkmcnt(4)
	v_mfma_f32_32x32x16_bf16 v[128:143], v[22:25], v[168:171], v[128:143]
	s_waitcnt lgkmcnt(3)
	v_mfma_f32_32x32x16_bf16 v[144:159], v[26:29], v[164:167], v[144:159]
	s_waitcnt lgkmcnt(2)
	v_mfma_f32_32x32x16_bf16 v[128:143], v[112:115], v[164:167], v[128:143]
	s_waitcnt lgkmcnt(1)
	v_mfma_f32_32x32x16_bf16 v[144:159], v[244:247], v[160:163], v[144:159]
	s_waitcnt lgkmcnt(0)
	v_mfma_f32_32x32x16_bf16 v[128:143], v[18:21], v[160:163], v[128:143]
	s_branch .LBB0_566
.Lst2_b:
	v_subrev_u32_e32 v243, 64, v197
	v_cvt_f32_i32_e32 v243, v243
	v_add_f32_e32 v17, 0, v96
	v_add_f32_e32 v17, v97, v17
	v_add_f32_e32 v17, v98, v17
	v_add_f32_e32 v17, v99, v17
	v_add_f32_e32 v17, v100, v17
	v_add_f32_e32 v17, v101, v17
	v_add_f32_e32 v17, v102, v17
	v_add_f32_e32 v17, v103, v17
	v_add_f32_e32 v17, v104, v17
	v_add_f32_e32 v17, v105, v17
	v_add_f32_e32 v17, v106, v17
	v_add_f32_e32 v17, v107, v17
	v_exp_f32_e32 v112, v116
	v_add_f32_e32 v17, v108, v17
	v_exp_f32_e32 v113, v117
	v_add_f32_e32 v17, v109, v17
	v_exp_f32_e32 v114, v118
	v_add_f32_e32 v17, v110, v17
	v_exp_f32_e32 v115, v119
	v_add_f32_e32 v17, v111, v17
	v_exp_f32_e32 v116, v120
	v_add_f32_e32 v17, v112, v17
	v_exp_f32_e32 v117, v121
	v_add_f32_e32 v17, v113, v17
	v_exp_f32_e32 v118, v122
	v_add_f32_e32 v17, v114, v17
	v_exp_f32_e32 v119, v123
	v_add_f32_e32 v17, v115, v17
	v_exp_f32_e32 v120, v124
	v_add_f32_e32 v17, v116, v17
	v_exp_f32_e32 v121, v125
	v_add_f32_e32 v17, v117, v17
	v_exp_f32_e32 v122, v126
	v_add_f32_e32 v17, v118, v17
	v_exp_f32_e32 v123, v127
	v_add_f32_e32 v17, v119, v17
	v_exp_f32_e32 v124, v198
	v_add_f32_e32 v17, v120, v17
	v_exp_f32_e32 v125, v199
	v_add_f32_e32 v17, v121, v17
	v_exp_f32_e32 v126, v242
	v_add_f32_e32 v17, v122, v17
	v_exp_f32_e32 v127, v196
	v_add_f32_e32 v17, v123, v17
	v_add_f32_e32 v17, v124, v17
	v_add_f32_e32 v17, v125, v17
	v_add_f32_e32 v17, v126, v17
	v_add_f32_e32 v17, v127, v17
	v_mov_b32_e32 v30, v17
	v_cvt_pk_bf16_f32 v18, v96, v97
	v_cvt_pk_bf16_f32 v19, v98, v99
	v_cvt_pk_bf16_f32 v20, v100, v101
	v_cvt_pk_bf16_f32 v21, v102, v103
	v_cvt_pk_bf16_f32 v22, v104, v105
	v_cvt_pk_bf16_f32 v23, v106, v107
	v_cvt_pk_bf16_f32 v24, v108, v109
	v_cvt_pk_bf16_f32 v25, v110, v111
	v_cvt_pk_bf16_f32 v26, v112, v113
	v_cvt_pk_bf16_f32 v27, v114, v115
	v_cvt_pk_bf16_f32 v28, v116, v117
	v_cvt_pk_bf16_f32 v29, v118, v119
	v_cvt_pk_bf16_f32 v196, v120, v121
	v_cvt_pk_bf16_f32 v197, v122, v123
	v_cvt_pk_bf16_f32 v198, v124, v125
	v_cvt_pk_bf16_f32 v199, v126, v127
	s_nop 1
	v_permlane32_swap_b32_e32 v17, v30
	v_permlane32_swap_b32_e32 v18, v20
	v_permlane32_swap_b32_e32 v19, v21
	v_permlane32_swap_b32_e32 v22, v24
	v_permlane32_swap_b32_e32 v23, v25
	v_permlane32_swap_b32_e32 v26, v28
	v_permlane32_swap_b32_e32 v27, v29
	v_permlane32_swap_b32_e32 v196, v198
	v_permlane32_swap_b32_e32 v197, v199
	s_and_b64 vcc, exec, s[0:1]
	s_cbranch_vccnz .Lst2_b_inact
	ds_read_b128 v[2:5], v235 offset:32768
	ds_read_b128 v[6:9], v235 offset:40960
	ds_read_b128 v[10:13], v236 offset:32768
	ds_read_b128 v[244:247], v236 offset:40960
	v_mov_b32_e32 v205, v204
	v_fma_f32 v145, s61, v243, s61
	v_add_f32_e32 v146, s61, v145
	v_mul_f32_e32 v144, s61, v243
	v_add_f32_e32 v147, s61, v146
	v_pk_add_f32 v[148:149], v[206:207], v[144:145]
	v_pk_add_f32 v[150:151], v[206:207], v[146:147]
	v_pk_add_f32 v[152:153], v[206:207], v[148:149]
	v_pk_add_f32 v[154:155], v[206:207], v[150:151]
	v_pk_add_f32 v[156:157], v[206:207], v[152:153]
	v_pk_add_f32 v[158:159], v[206:207], v[154:155]
	v_pk_add_f32 v[128:129], v[14:15], v[144:145]
	v_pk_add_f32 v[132:133], v[204:205], v[148:149]
	v_pk_add_f32 v[136:137], v[204:205], v[152:153]
	v_pk_add_f32 v[130:131], v[204:205], v[146:147]
	v_pk_add_f32 v[140:141], v[204:205], v[156:157]
	v_pk_add_f32 v[134:135], v[204:205], v[150:151]
	v_pk_add_f32 v[138:139], v[204:205], v[154:155]
	v_pk_add_f32 v[142:143], v[204:205], v[158:159]
	s_waitcnt lgkmcnt(3)
	v_mfma_f32_32x32x16_bf16 v[144:159], v[2:5], v[188:191], v[144:159]
	ds_read_b128 v[2:5], v237 offset:32768
	s_waitcnt lgkmcnt(3)
	v_mfma_f32_32x32x16_bf16 v[128:143], v[6:9], v[188:191], v[128:143]
	ds_read_b128 v[6:9], v237 offset:40960
	s_waitcnt lgkmcnt(3)
	v_mfma_f32_32x32x16_bf16 v[144:159], v[10:13], v[184:187], v[144:159]
	ds_read_b128 v[10:13], v238 offset:32768
	s_waitcnt lgkmcnt(3)
	v_mfma_f32_32x32x16_bf16 v[128:143], v[244:247], v[184:187], v[128:143]
	ds_read_b128 v[244:247], v238 offset:40960
	s_waitcnt lgkmcnt(3)
	v_mfma_f32_32x32x16_bf16 v[144:159], v[2:5], v[180:183], v[144:159]
	ds_read_b128 v[2:5], v235 offset:32896
	s_waitcnt lgkmcnt(3)
	v_mfma_f32_32x32x16_bf16 v[128:143], v[6:9], v[180:183], v[128:143]
	ds_read_b128 v[6:9], v235 offset:41088
	s_waitcnt lgkmcnt(3)
	v_mfma_f32_32x32x16_bf16 v[144:159], v[10:13], v[176:179], v[144:159]
	ds_read_b128 v[10:13], v236 offset:32896
	s_waitcnt lgkmcnt(3)
	v_mfma_f32_32x32x16_bf16 v[128:143], v[244:247], v[176:179], v[128:143]
	ds_read_b128 v[244:247], v236 offset:41088
	s_waitcnt lgkmcnt(3)
	v_mfma_f32_32x32x16_bf16 v[144:159], v[2:5], v[172:175], v[144:159]
	ds_read_b128 v[2:5], v237 offset:32896
	s_waitcnt lgkmcnt(3)
	v_mfma_f32_32x32x16_bf16 v[128:143], v[6:9], v[172:175], v[128:143]
	ds_read_b128 v[6:9], v237 offset:41088
	s_waitcnt lgkmcnt(3)
	v_mfma_f32_32x32x16_bf16 v[144:159], v[10:13], v[168:171], v[144:159]
	ds_read_b128 v[10:13], v238 offset:32896
	s_waitcnt lgkmcnt(3)
	v_mfma_f32_32x32x16_bf16 v[128:143], v[244:247], v[168:171], v[128:143]
	ds_read_b128 v[244:247], v238 offset:41088
	s_waitcnt lgkmcnt(3)
	v_mfma_f32_32x32x16_bf16 v[144:159], v[2:5], v[164:167], v[144:159]
	s_waitcnt lgkmcnt(2)
	v_mfma_f32_32x32x16_bf16 v[128:143], v[6:9], v[164:167], v[128:143]
	s_waitcnt lgkmcnt(1)
	v_mfma_f32_32x32x16_bf16 v[144:159], v[10:13], v[160:163], v[144:159]
	s_waitcnt lgkmcnt(0)
	v_mfma_f32_32x32x16_bf16 v[128:143], v[244:247], v[160:163], v[128:143]
	s_branch .Lst2_join
